# hoist compiler vmcnt(0) out of P1 GEMM K-loop to preheader
# speedup vs baseline: 1.0151x; 1.0151x over previous
; #define PG8_STAGE(bufoff, gbase, voff) do { _Pragma("unroll") for (int _i = 0; _i < 2; ++_i) \
;         __builtin_amdgcn_global_load_lds((const unsigned*)((const char*)(gbase) + (voff)[_i]), (PG8_LAS unsigned*)(lds + (bufoff) + ldsw + _i * 8192), 16, 0, 0); } while (0)
; #define PG8_LDA(dst, b, h) do { _Pragma("unroll") for (int m = 0; m < 4; ++m) _Pragma("unroll") for (int k = 0; k < 2; ++k) dst[m][k] = *(const PG8_LAS bf16x8*)(lds + PG8_SA(b, h) + aoff + m * 2048 + k * 1024); } while (0)
; #define PG8_LDB(dst, b, h) do { _Pragma("unroll") for (int n = 0; n < 2; ++n) _Pragma("unroll") for (int k = 0; k < 2; ++k) dst[n][k] = *(const PG8_LAS bf16x8*)(lds + PG8_SB(b, h) + boff + n * 2048 + k * 1024); } while (0)
; #define PG8_WAIT_V(n) asm volatile("s_waitcnt vmcnt(" #n ")" ::: "memory")
; #define PG8_WAIT_L(n) asm volatile("s_waitcnt lgkmcnt(" #n ")" ::: "memory")
; #define PG8_BAR __builtin_amdgcn_s_barrier()
; #define PG8_SCHED __builtin_amdgcn_sched_barrier(0)
; template <class Epi, class Sched, bool ALIGN_EPI = false, bool SP2 = false>
; __device__ __forceinline__ void gemm_phase(PG8_LAS unsigned char* lds, const Gemm g, const Sched& S, const Epi& E) {
;     ...
;         const bool has_next = S.next(ui + 1, nxt);
;         const char* nA = has_next ? (const char*)g.A + (size_t)nxt.pm * tstep : cA; const char* nB = has_next ? (const char*)g.Bt + (size_t)nxt.pn * tstep : cB;
;         for (int t = 0; t < nt; t += 2) {
;             const bool last = (t == nt - 2);
;             const char* a1 = cA + (size_t)(t + 1) * kstep;
;             const char* a2 = last ? nA : cA + (size_t)(t + 2) * kstep; const char* b2 = last ? nB : cB + (size_t)(t + 2) * kstep;
;             const char* a3 = a2 + kstep; const char* b3 = b2 + kstep;
;             if (last && has_next) S.a_ready(nxt);
;             if constexpr (SP2) {
;             PG8_LDB(B0, 0, 0); PG8_LDB(B1, 0, 1); PG8_SCHED; PG8_LDA(At, 0, 0); PG8_STAGE(PG8_SA(1, 1), a1 + hstep, voffA);
;             PG8_WAIT_V(8); PG8_WAIT_L(0); PG8_BAR; PG8_MMA(0, 0, At, B0); PG8_MMA(0, 1, At, B1); PG8_BAR; PG8_SCHED;
;     ...
; #pragma unroll
;         for (int a = 0; a < 2; ++a)
; #pragma unroll
;             for (int b = 0; b < 2; ++b)
; #pragma unroll
;                 for (int m = 0; m < 4; ++m)
; #pragma unroll
;                     for (int n = 0; n < 2; ++n) acc[a][b][m][n] = (f32x4){0.f, 0.f, 0.f, 0.f};
.LBB0_212:
	s_ashr_i32 s31, s30, 31
	s_lshl_b64 s[14:15], s[30:31], 20
	s_add_u32 s34, s57, s14
	s_addc_u32 s35, s58, s15
	s_and_b64 s[14:15], s[8:9], exec
	s_cselect_b32 s16, s35, s13
	s_cselect_b32 s17, s34, s12
	s_ashr_i32 s29, s28, 31
	s_lshl_b64 s[14:15], s[28:29], 20
	s_add_u32 s36, s59, s14
	s_addc_u32 s37, s60, s15
	s_and_b64 s[14:15], s[8:9], exec
	s_cselect_b32 s29, s37, s11
	s_cselect_b32 s31, s36, s10
	s_add_u32 s38, s10, 0x100
	s_addc_u32 s39, s11, 0
	s_add_u32 s10, s12, 0x80080
	v_mov_b32_e32 v2, 0
	s_addc_u32 s11, s13, 0
	s_mov_b32 s40, -2
	v_mov_b32_e32 v3, v2
	v_mov_b32_e32 v4, v2
	v_mov_b32_e32 v5, v2
	v_mov_b32_e32 v6, v2
	v_mov_b32_e32 v7, v2
	v_mov_b32_e32 v8, v2
	v_mov_b32_e32 v9, v2
	v_mov_b32_e32 v26, v2
	v_mov_b32_e32 v27, v2
	v_mov_b32_e32 v28, v2
	v_mov_b32_e32 v29, v2
	v_mov_b32_e32 v30, v2
	v_mov_b32_e32 v31, v2
	v_mov_b32_e32 v32, v2
	v_mov_b32_e32 v33, v2
	v_mov_b32_e32 v42, v2
	v_mov_b32_e32 v43, v2
	v_mov_b32_e32 v44, v2
	v_mov_b32_e32 v45, v2
	v_mov_b32_e32 v46, v2
	v_mov_b32_e32 v47, v2
	v_mov_b32_e32 v48, v2
	v_mov_b32_e32 v49, v2
	v_mov_b32_e32 v58, v2
	v_mov_b32_e32 v59, v2
	v_mov_b32_e32 v60, v2
	v_mov_b32_e32 v61, v2
	v_mov_b32_e32 v62, v2
	v_mov_b32_e32 v63, v2
	v_mov_b32_e32 v64, v2
	v_mov_b32_e32 v65, v2
	v_mov_b32_e32 v10, v2
	v_mov_b32_e32 v11, v2
	v_mov_b32_e32 v12, v2
	v_mov_b32_e32 v13, v2
	v_mov_b32_e32 v14, v2
	v_mov_b32_e32 v15, v2
	v_mov_b32_e32 v16, v2
	v_mov_b32_e32 v17, v2
	v_mov_b32_e32 v34, v2
	v_mov_b32_e32 v35, v2
	v_mov_b32_e32 v36, v2
	v_mov_b32_e32 v37, v2
	v_mov_b32_e32 v38, v2
	v_mov_b32_e32 v39, v2
	v_mov_b32_e32 v40, v2
	v_mov_b32_e32 v41, v2
	v_mov_b32_e32 v50, v2
	v_mov_b32_e32 v51, v2
	v_mov_b32_e32 v52, v2
	v_mov_b32_e32 v53, v2
	v_mov_b32_e32 v54, v2
	v_mov_b32_e32 v55, v2
	v_mov_b32_e32 v56, v2
	v_mov_b32_e32 v57, v2
	v_mov_b32_e32 v66, v2
	v_mov_b32_e32 v67, v2
	v_mov_b32_e32 v68, v2
	v_mov_b32_e32 v69, v2
	v_mov_b32_e32 v70, v2
	v_mov_b32_e32 v71, v2
	v_mov_b32_e32 v72, v2
	v_mov_b32_e32 v73, v2
	v_mov_b32_e32 v74, v2
	v_mov_b32_e32 v75, v2
	v_mov_b32_e32 v76, v2
	v_mov_b32_e32 v77, v2
	v_mov_b32_e32 v78, v2
	v_mov_b32_e32 v79, v2
	v_mov_b32_e32 v80, v2
	v_mov_b32_e32 v81, v2
	v_mov_b32_e32 v90, v2
	v_mov_b32_e32 v91, v2
	v_mov_b32_e32 v92, v2
	v_mov_b32_e32 v93, v2
	v_mov_b32_e32 v94, v2
	v_mov_b32_e32 v95, v2
	v_mov_b32_e32 v96, v2
	v_mov_b32_e32 v97, v2
	v_mov_b32_e32 v106, v2
	v_mov_b32_e32 v107, v2
	v_mov_b32_e32 v108, v2
	v_mov_b32_e32 v109, v2
	v_mov_b32_e32 v110, v2
	v_mov_b32_e32 v111, v2
	v_mov_b32_e32 v112, v2
	v_mov_b32_e32 v113, v2
	v_mov_b32_e32 v122, v2
	v_mov_b32_e32 v123, v2
	v_mov_b32_e32 v124, v2
	v_mov_b32_e32 v125, v2
	v_mov_b32_e32 v126, v2
	v_mov_b32_e32 v127, v2
	v_mov_b32_e32 v128, v2
	v_mov_b32_e32 v129, v2
	v_mov_b32_e32 v82, v2
	v_mov_b32_e32 v83, v2
	v_mov_b32_e32 v84, v2
	v_mov_b32_e32 v85, v2
	v_mov_b32_e32 v86, v2
	v_mov_b32_e32 v87, v2
	v_mov_b32_e32 v88, v2
	v_mov_b32_e32 v89, v2
	v_mov_b32_e32 v98, v2
	v_mov_b32_e32 v99, v2
	v_mov_b32_e32 v100, v2
	v_mov_b32_e32 v101, v2
	v_mov_b32_e32 v102, v2
	v_mov_b32_e32 v103, v2
	v_mov_b32_e32 v104, v2
	v_mov_b32_e32 v105, v2
	v_mov_b32_e32 v114, v2
	v_mov_b32_e32 v115, v2
	v_mov_b32_e32 v116, v2
	v_mov_b32_e32 v117, v2
	v_mov_b32_e32 v118, v2
	v_mov_b32_e32 v119, v2
	v_mov_b32_e32 v120, v2
	v_mov_b32_e32 v121, v2
	v_mov_b32_e32 v130, v2
	v_mov_b32_e32 v131, v2
	v_mov_b32_e32 v132, v2
	v_mov_b32_e32 v133, v2
	v_mov_b32_e32 v134, v2
	v_mov_b32_e32 v135, v2
	v_mov_b32_e32 v136, v2
	v_mov_b32_e32 v137, v2
	s_mov_b64 s[46:47], 0x80
	s_waitcnt vmcnt(0)
.LBB0_213:
	s_add_u32 s12, s10, 0xfff80080
	s_addc_u32 s13, s11, -1
	s_add_i32 s41, 0, 0x10000
	s_cmp_eq_u32 s40, 28
	s_cselect_b32 s15, s16, s13
	s_cselect_b32 s14, s17, s12
	v_add_u32_e32 v0, s41, v196
	s_cselect_b32 s13, s29, s39
	s_cselect_b32 s12, s31, s38
	s_add_i32 s43, 0, 0x14000
	ds_read_b128 v[18:21], v0
	ds_read_b128 v[22:25], v0 offset:1024
	ds_read_b128 v[160:163], v0 offset:2048
	ds_read_b128 v[164:167], v0 offset:3072
	v_add_u32_e32 v0, s43, v196
	ds_read_b128 v[168:171], v0
	ds_read_b128 v[172:175], v0 offset:1024
	ds_read_b128 v[176:179], v0 offset:2048
	ds_read_b128 v[180:183], v0 offset:3072
	v_lshl_add_u64 v[184:185], s[10:11], 0, v[158:159]
	s_add_i32 m0, s61, 0xc000
	ds_read_b128 v[198:201], v197
	ds_read_b128 v[202:205], v197 offset:1024
	ds_read_b128 v[206:209], v197 offset:2048
	ds_read_b128 v[210:213], v197 offset:3072
	ds_read_b128 v[214:217], v197 offset:4096
	ds_read_b128 v[232:235], v197 offset:5120
	ds_read_b128 v[236:239], v197 offset:6144
	ds_read_b128 v[240:243], v197 offset:7168
	global_load_lds_dwordx4 v[184:185], off
	v_lshl_add_u64 v[184:185], s[10:11], 0, v[156:157]
	s_add_i32 m0, s61, 0xe000
	s_nop 0
	global_load_lds_dwordx4 v[184:185], off
	s_waitcnt vmcnt(8)
	s_waitcnt lgkmcnt(0)
	s_barrier
; #define PG8_STAGE(bufoff, gbase, voff) do { _Pragma("unroll") for (int _i = 0; _i < 2; ++_i) \
;         __builtin_amdgcn_global_load_lds((const unsigned*)((const char*)(gbase) + (voff)[_i]), (PG8_LAS unsigned*)(lds + (bufoff) + ldsw + _i * 8192), 16, 0, 0); } while (0)
; #define PG8_LDA(dst, b, h) do { _Pragma("unroll") for (int m = 0; m < 4; ++m) _Pragma("unroll") for (int k = 0; k < 2; ++k) dst[m][k] = *(const PG8_LAS bf16x8*)(lds + PG8_SA(b, h) + aoff + m * 2048 + k * 1024); } while (0)
; #define PG8_MMA(ai, bj, At, Bt) do { __builtin_amdgcn_s_setprio(1); _Pragma("unroll") for (int m = 0; m < 4; ++m) _Pragma("unroll") for (int n = 0; n < 2; ++n) _Pragma("unroll") for (int k = 0; k < 2; ++k) \
;         acc[ai][bj][m][n] = __builtin_amdgcn_mfma_f32_16x16x32_bf16(Bt[n][k], At[m][k], acc[ai][bj][m][n], 0, 0, 0); __builtin_amdgcn_s_setprio(0); } while (0)
; #define PG8_WAIT_V(n) asm volatile("s_waitcnt vmcnt(" #n ")" ::: "memory")
; #define PG8_WAIT_L(n) asm volatile("s_waitcnt lgkmcnt(" #n ")" ::: "memory")
; #define PG8_BAR __builtin_amdgcn_s_barrier()
; #define PG8_SCHED __builtin_amdgcn_sched_barrier(0)
; template <class Epi, class Sched, bool ALIGN_EPI = false, bool SP2 = false>
; __device__ __forceinline__ void gemm_phase(PG8_LAS unsigned char* lds, const Gemm g, const Sched& S, const Epi& E) {
;     ...
;             PG8_WAIT_V(8); PG8_WAIT_L(0); PG8_BAR; PG8_MMA(0, 0, At, B0); PG8_MMA(0, 1, At, B1); PG8_BAR; PG8_SCHED;
;             PG8_LDA(At, 0, 1); PG8_STAGE(PG8_SB(0, 0), b2, voffB); PG8_STAGE(PG8_SB(0, 1), b2 + hstep, voffB); PG8_STAGE(PG8_SA(0, 0), a2, voffA);
;             PG8_WAIT_V(8); PG8_WAIT_L(0); PG8_BAR; PG8_MMA(1, 0, At, B0); PG8_MMA(1, 1, At, B1); PG8_BAR; PG8_SCHED;
	s_setprio 1
	s_waitcnt lgkmcnt(0)
	v_mfma_f32_16x16x32_bf16 v[134:137], v[18:21], v[198:201], v[134:137]
	v_mfma_f32_16x16x32_bf16 v[130:133], v[160:163], v[198:201], v[130:133]
	v_mfma_f32_16x16x32_bf16 v[118:121], v[18:21], v[206:209], v[118:121]
	v_mfma_f32_16x16x32_bf16 v[114:117], v[160:163], v[206:209], v[114:117]
	v_mfma_f32_16x16x32_bf16 v[102:105], v[18:21], v[214:217], v[102:105]
	v_mfma_f32_16x16x32_bf16 v[98:101], v[160:163], v[214:217], v[98:101]
	v_mfma_f32_16x16x32_bf16 v[86:89], v[18:21], v[236:239], v[86:89]
	v_mfma_f32_16x16x32_bf16 v[82:85], v[160:163], v[236:239], v[82:85]
	v_mfma_f32_16x16x32_bf16 v[134:137], v[22:25], v[202:205], v[134:137]
	v_mfma_f32_16x16x32_bf16 v[130:133], v[164:167], v[202:205], v[130:133]
	v_mfma_f32_16x16x32_bf16 v[118:121], v[22:25], v[210:213], v[118:121]
	v_mfma_f32_16x16x32_bf16 v[114:117], v[164:167], v[210:213], v[114:117]
	v_mfma_f32_16x16x32_bf16 v[102:105], v[22:25], v[232:235], v[102:105]
	v_mfma_f32_16x16x32_bf16 v[98:101], v[164:167], v[232:235], v[98:101]
	v_mfma_f32_16x16x32_bf16 v[86:89], v[22:25], v[240:243], v[86:89]
	v_mfma_f32_16x16x32_bf16 v[82:85], v[164:167], v[240:243], v[82:85]
	s_setprio 0
	s_setprio 1
	v_mfma_f32_16x16x32_bf16 v[126:129], v[168:171], v[198:201], v[126:129]
	v_mfma_f32_16x16x32_bf16 v[122:125], v[176:179], v[198:201], v[122:125]
	v_mfma_f32_16x16x32_bf16 v[110:113], v[168:171], v[206:209], v[110:113]
	v_mfma_f32_16x16x32_bf16 v[106:109], v[176:179], v[206:209], v[106:109]
	v_mfma_f32_16x16x32_bf16 v[94:97], v[168:171], v[214:217], v[94:97]
	v_mfma_f32_16x16x32_bf16 v[90:93], v[176:179], v[214:217], v[90:93]
	v_mfma_f32_16x16x32_bf16 v[78:81], v[168:171], v[236:239], v[78:81]
	v_mfma_f32_16x16x32_bf16 v[74:77], v[176:179], v[236:239], v[74:77]
	v_mfma_f32_16x16x32_bf16 v[126:129], v[172:175], v[202:205], v[126:129]
	v_mfma_f32_16x16x32_bf16 v[122:125], v[180:183], v[202:205], v[122:125]
	v_mfma_f32_16x16x32_bf16 v[110:113], v[172:175], v[210:213], v[110:113]
	v_mfma_f32_16x16x32_bf16 v[106:109], v[180:183], v[210:213], v[106:109]
	v_mfma_f32_16x16x32_bf16 v[94:97], v[172:175], v[232:235], v[94:97]
	v_mfma_f32_16x16x32_bf16 v[90:93], v[180:183], v[232:235], v[90:93]
	v_mfma_f32_16x16x32_bf16 v[78:81], v[172:175], v[240:243], v[78:81]
	v_mfma_f32_16x16x32_bf16 v[74:77], v[180:183], v[240:243], v[74:77]
	s_setprio 0
	s_barrier
	s_add_i32 s41, s41, s56
	v_lshl_add_u64 v[184:185], s[12:13], 0, v[142:143]
	s_mov_b32 m0, s41
	ds_read_b128 v[198:201], v197 offset:16384
	ds_read_b128 v[202:205], v197 offset:17408
	ds_read_b128 v[206:209], v197 offset:18432
	ds_read_b128 v[210:213], v197 offset:19456
	ds_read_b128 v[214:217], v197 offset:20480
	ds_read_b128 v[232:235], v197 offset:21504
	ds_read_b128 v[236:239], v197 offset:22528
	ds_read_b128 v[240:243], v197 offset:23552
	global_load_lds_dwordx4 v[184:185], off
	s_add_i32 m0, s41, 0x2000
	s_add_u32 s44, s12, 0x80000
	v_lshl_add_u64 v[190:191], s[12:13], 0, v[138:139]
	s_addc_u32 s45, s13, 0
	s_add_i32 s41, s43, s56
	global_load_lds_dwordx4 v[190:191], off
	v_lshl_add_u64 v[192:193], s[44:45], 0, v[142:143]
	s_mov_b32 m0, s41
	v_lshl_add_u64 v[194:195], s[14:15], 0, v[140:141]
	global_load_lds_dwordx4 v[192:193], off
	v_lshl_add_u64 v[192:193], s[44:45], 0, v[138:139]
	s_add_i32 m0, s41, 0x2000
	s_nop 0
	global_load_lds_dwordx4 v[192:193], off
	v_lshl_add_u64 v[192:193], s[14:15], 0, v[144:145]
	s_mov_b32 m0, s61
	s_nop 0
	global_load_lds_dwordx4 v[192:193], off
	s_mov_b32 m0, s62
	s_nop 0
	global_load_lds_dwordx4 v[194:195], off
	s_waitcnt vmcnt(8)
	s_waitcnt lgkmcnt(0)
	s_barrier
	s_setprio 1
	s_waitcnt lgkmcnt(0)
	v_mfma_f32_16x16x32_bf16 v[70:73], v[18:21], v[198:201], v[70:73]
	v_mfma_f32_16x16x32_bf16 v[66:69], v[160:163], v[198:201], v[66:69]
	v_mfma_f32_16x16x32_bf16 v[54:57], v[18:21], v[206:209], v[54:57]
	v_mfma_f32_16x16x32_bf16 v[50:53], v[160:163], v[206:209], v[50:53]
	v_mfma_f32_16x16x32_bf16 v[38:41], v[18:21], v[214:217], v[38:41]
	v_mfma_f32_16x16x32_bf16 v[34:37], v[160:163], v[214:217], v[34:37]
	v_mfma_f32_16x16x32_bf16 v[14:17], v[18:21], v[236:239], v[14:17]
	v_mfma_f32_16x16x32_bf16 v[10:13], v[160:163], v[236:239], v[10:13]
	v_mfma_f32_16x16x32_bf16 v[70:73], v[22:25], v[202:205], v[70:73]
	v_mfma_f32_16x16x32_bf16 v[66:69], v[164:167], v[202:205], v[66:69]
	v_mfma_f32_16x16x32_bf16 v[54:57], v[22:25], v[210:213], v[54:57]
	v_mfma_f32_16x16x32_bf16 v[50:53], v[164:167], v[210:213], v[50:53]
	v_mfma_f32_16x16x32_bf16 v[38:41], v[22:25], v[232:235], v[38:41]
	v_mfma_f32_16x16x32_bf16 v[34:37], v[164:167], v[232:235], v[34:37]
	v_mfma_f32_16x16x32_bf16 v[14:17], v[22:25], v[240:243], v[14:17]
	v_mfma_f32_16x16x32_bf16 v[10:13], v[164:167], v[240:243], v[10:13]
	s_setprio 0
	s_setprio 1
	v_mfma_f32_16x16x32_bf16 v[46:49], v[168:171], v[206:209], v[46:49]
	v_mfma_f32_16x16x32_bf16 v[42:45], v[176:179], v[206:209], v[42:45]
	v_mfma_f32_16x16x32_bf16 v[30:33], v[168:171], v[214:217], v[30:33]
	v_mfma_f32_16x16x32_bf16 v[26:29], v[176:179], v[214:217], v[26:29]
	v_mfma_f32_16x16x32_bf16 v[6:9], v[168:171], v[236:239], v[6:9]
	v_mfma_f32_16x16x32_bf16 v[2:5], v[176:179], v[236:239], v[2:5]
	v_mfma_f32_16x16x32_bf16 v[18:21], v[168:171], v[198:201], v[62:65]
	v_mfma_f32_16x16x32_bf16 v[22:25], v[176:179], v[198:201], v[58:61]
	v_mfma_f32_16x16x32_bf16 v[46:49], v[172:175], v[210:213], v[46:49]
	v_mfma_f32_16x16x32_bf16 v[42:45], v[180:183], v[210:213], v[42:45]
	v_mfma_f32_16x16x32_bf16 v[30:33], v[172:175], v[232:235], v[30:33]
	v_mfma_f32_16x16x32_bf16 v[26:29], v[180:183], v[232:235], v[26:29]
	v_mfma_f32_16x16x32_bf16 v[6:9], v[172:175], v[240:243], v[6:9]
	v_mfma_f32_16x16x32_bf16 v[2:5], v[180:183], v[240:243], v[2:5]
	v_mfma_f32_16x16x32_bf16 v[18:21], v[172:175], v[202:205], v[18:21]
	v_mfma_f32_16x16x32_bf16 v[22:25], v[180:183], v[202:205], v[22:25]
	s_setprio 0
	s_barrier
; #define PG8_STAGE(bufoff, gbase, voff) do { _Pragma("unroll") for (int _i = 0; _i < 2; ++_i) \
;         __builtin_amdgcn_global_load_lds((const unsigned*)((const char*)(gbase) + (voff)[_i]), (PG8_LAS unsigned*)(lds + (bufoff) + ldsw + _i * 8192), 16, 0, 0); } while (0)
; #define PG8_LDA(dst, b, h) do { _Pragma("unroll") for (int m = 0; m < 4; ++m) _Pragma("unroll") for (int k = 0; k < 2; ++k) dst[m][k] = *(const PG8_LAS bf16x8*)(lds + PG8_SA(b, h) + aoff + m * 2048 + k * 1024); } while (0)
; #define PG8_LDB(dst, b, h) do { _Pragma("unroll") for (int n = 0; n < 2; ++n) _Pragma("unroll") for (int k = 0; k < 2; ++k) dst[n][k] = *(const PG8_LAS bf16x8*)(lds + PG8_SB(b, h) + boff + n * 2048 + k * 1024); } while (0)
; #define PG8_MMA(ai, bj, At, Bt) do { __builtin_amdgcn_s_setprio(1); _Pragma("unroll") for (int m = 0; m < 4; ++m) _Pragma("unroll") for (int n = 0; n < 2; ++n) _Pragma("unroll") for (int k = 0; k < 2; ++k) \
;         acc[ai][bj][m][n] = __builtin_amdgcn_mfma_f32_16x16x32_bf16(Bt[n][k], At[m][k], acc[ai][bj][m][n], 0, 0, 0); __builtin_amdgcn_s_setprio(0); } while (0)
; #define PG8_WAIT_V(n) asm volatile("s_waitcnt vmcnt(" #n ")" ::: "memory")
; #define PG8_WAIT_L(n) asm volatile("s_waitcnt lgkmcnt(" #n ")" ::: "memory")
; #define PG8_BAR __builtin_amdgcn_s_barrier()
; #define PG8_SCHED __builtin_amdgcn_sched_barrier(0)
; template <class Epi, class Sched, bool ALIGN_EPI = false, bool SP2 = false>
; __device__ __forceinline__ void gemm_phase(PG8_LAS unsigned char* lds, const Gemm g, const Sched& S, const Epi& E) {
;     ...
;             PG8_LDB(B0, 1, 0); PG8_LDB(B1, 1, 1); PG8_SCHED; PG8_LDA(At, 1, 0); PG8_STAGE(PG8_SA(0, 1), a2 + hstep, voffA);
;             PG8_WAIT_V(8); PG8_WAIT_L(0); PG8_BAR; PG8_MMA(0, 0, At, B0); PG8_MMA(0, 1, At, B1); PG8_BAR; PG8_SCHED;
	s_add_i32 s41, 0, 0x18000
	v_add_u32_e32 v0, s41, v196
	s_add_i32 s43, 0, 0x1c000
	ds_read_b128 v[58:61], v0
	ds_read_b128 v[62:65], v0 offset:1024
	ds_read_b128 v[160:163], v0 offset:2048
	ds_read_b128 v[164:167], v0 offset:3072
	v_add_u32_e32 v0, s43, v196
	ds_read_b128 v[168:171], v0
	ds_read_b128 v[172:175], v0 offset:1024
	ds_read_b128 v[176:179], v0 offset:2048
	ds_read_b128 v[180:183], v0 offset:3072
	s_add_u32 s14, s14, 0x80000
	s_addc_u32 s15, s15, 0
	s_mov_b32 m0, s63
	v_lshl_add_u64 v[218:219], s[14:15], 0, v[144:145]
	ds_read_b128 v[198:201], v197 offset:32768
	ds_read_b128 v[202:205], v197 offset:33792
	ds_read_b128 v[206:209], v197 offset:34816
	ds_read_b128 v[210:213], v197 offset:35840
	ds_read_b128 v[214:217], v197 offset:36864
	ds_read_b128 v[232:235], v197 offset:37888
	ds_read_b128 v[236:239], v197 offset:38912
	ds_read_b128 v[240:243], v197 offset:39936
	global_load_lds_dwordx4 v[218:219], off
	v_lshl_add_u64 v[218:219], s[14:15], 0, v[140:141]
	s_mov_b32 m0, s64
	s_nop 0
	global_load_lds_dwordx4 v[218:219], off
	s_waitcnt vmcnt(8)
	s_waitcnt lgkmcnt(0)
	s_barrier
	s_setprio 1
	s_waitcnt lgkmcnt(0)
	v_mfma_f32_16x16x32_bf16 v[134:137], v[58:61], v[198:201], v[134:137]
	v_mfma_f32_16x16x32_bf16 v[130:133], v[160:163], v[198:201], v[130:133]
	v_mfma_f32_16x16x32_bf16 v[118:121], v[58:61], v[206:209], v[118:121]
	v_mfma_f32_16x16x32_bf16 v[114:117], v[160:163], v[206:209], v[114:117]
	v_mfma_f32_16x16x32_bf16 v[102:105], v[58:61], v[214:217], v[102:105]
	v_mfma_f32_16x16x32_bf16 v[98:101], v[160:163], v[214:217], v[98:101]
	v_mfma_f32_16x16x32_bf16 v[86:89], v[58:61], v[236:239], v[86:89]
	v_mfma_f32_16x16x32_bf16 v[82:85], v[160:163], v[236:239], v[82:85]
	v_mfma_f32_16x16x32_bf16 v[134:137], v[62:65], v[202:205], v[134:137]
	v_mfma_f32_16x16x32_bf16 v[130:133], v[164:167], v[202:205], v[130:133]
	v_mfma_f32_16x16x32_bf16 v[118:121], v[62:65], v[210:213], v[118:121]
	v_mfma_f32_16x16x32_bf16 v[114:117], v[164:167], v[210:213], v[114:117]
	v_mfma_f32_16x16x32_bf16 v[102:105], v[62:65], v[232:235], v[102:105]
	v_mfma_f32_16x16x32_bf16 v[98:101], v[164:167], v[232:235], v[98:101]
	v_mfma_f32_16x16x32_bf16 v[86:89], v[62:65], v[240:243], v[86:89]
	v_mfma_f32_16x16x32_bf16 v[82:85], v[164:167], v[240:243], v[82:85]
	s_setprio 0
	s_setprio 1
	v_mfma_f32_16x16x32_bf16 v[126:129], v[168:171], v[198:201], v[126:129]
	v_mfma_f32_16x16x32_bf16 v[122:125], v[176:179], v[198:201], v[122:125]
	v_mfma_f32_16x16x32_bf16 v[110:113], v[168:171], v[206:209], v[110:113]
	v_mfma_f32_16x16x32_bf16 v[106:109], v[176:179], v[206:209], v[106:109]
	v_mfma_f32_16x16x32_bf16 v[94:97], v[168:171], v[214:217], v[94:97]
	v_mfma_f32_16x16x32_bf16 v[90:93], v[176:179], v[214:217], v[90:93]
	v_mfma_f32_16x16x32_bf16 v[78:81], v[168:171], v[236:239], v[78:81]
	v_mfma_f32_16x16x32_bf16 v[74:77], v[176:179], v[236:239], v[74:77]
	v_mfma_f32_16x16x32_bf16 v[126:129], v[172:175], v[202:205], v[126:129]
	v_mfma_f32_16x16x32_bf16 v[122:125], v[180:183], v[202:205], v[122:125]
	v_mfma_f32_16x16x32_bf16 v[110:113], v[172:175], v[210:213], v[110:113]
	v_mfma_f32_16x16x32_bf16 v[106:109], v[180:183], v[210:213], v[106:109]
	v_mfma_f32_16x16x32_bf16 v[94:97], v[172:175], v[232:235], v[94:97]
	v_mfma_f32_16x16x32_bf16 v[90:93], v[180:183], v[232:235], v[90:93]
	v_mfma_f32_16x16x32_bf16 v[78:81], v[172:175], v[240:243], v[78:81]
	v_mfma_f32_16x16x32_bf16 v[74:77], v[180:183], v[240:243], v[74:77]
	s_setprio 0
	s_barrier
; #define PG8_STAGE(bufoff, gbase, voff) do { _Pragma("unroll") for (int _i = 0; _i < 2; ++_i) \
;         __builtin_amdgcn_global_load_lds((const unsigned*)((const char*)(gbase) + (voff)[_i]), (PG8_LAS unsigned*)(lds + (bufoff) + ldsw + _i * 8192), 16, 0, 0); } while (0)
; #define PG8_LDA(dst, b, h) do { _Pragma("unroll") for (int m = 0; m < 4; ++m) _Pragma("unroll") for (int k = 0; k < 2; ++k) dst[m][k] = *(const PG8_LAS bf16x8*)(lds + PG8_SA(b, h) + aoff + m * 2048 + k * 1024); } while (0)
; #define PG8_MMA(ai, bj, At, Bt) do { __builtin_amdgcn_s_setprio(1); _Pragma("unroll") for (int m = 0; m < 4; ++m) _Pragma("unroll") for (int n = 0; n < 2; ++n) _Pragma("unroll") for (int k = 0; k < 2; ++k) \
;         acc[ai][bj][m][n] = __builtin_amdgcn_mfma_f32_16x16x32_bf16(Bt[n][k], At[m][k], acc[ai][bj][m][n], 0, 0, 0); __builtin_amdgcn_s_setprio(0); } while (0)
; #define PG8_WAIT_V(n) asm volatile("s_waitcnt vmcnt(" #n ")" ::: "memory")
; #define PG8_WAIT_L(n) asm volatile("s_waitcnt lgkmcnt(" #n ")" ::: "memory")
; #define PG8_BAR __builtin_amdgcn_s_barrier()
; #define PG8_SCHED __builtin_amdgcn_sched_barrier(0)
; template <class Epi, class Sched, bool ALIGN_EPI = false, bool SP2 = false>
; __device__ __forceinline__ void gemm_phase(PG8_LAS unsigned char* lds, const Gemm g, const Sched& S, const Epi& E) {
;     ...
;         for (int t = 0; t < nt; t += 2) {
;     ...
;             PG8_LDA(At, 1, 1); PG8_STAGE(PG8_SB(1, 0), b3, voffB); PG8_STAGE(PG8_SB(1, 1), b3 + hstep, voffB); PG8_STAGE(PG8_SA(1, 0), a3, voffA);
;             PG8_WAIT_V(8); PG8_WAIT_L(0); PG8_BAR; PG8_MMA(1, 0, At, B0); PG8_MMA(1, 1, At, B1); PG8_BAR; PG8_SCHED;
	s_add_i32 s14, s41, s56
	v_lshl_add_u64 v[184:185], v[184:185], 0, s[46:47]
	s_mov_b32 m0, s14
	ds_read_b128 v[198:201], v197 offset:49152
	ds_read_b128 v[202:205], v197 offset:50176
	ds_read_b128 v[206:209], v197 offset:51200
	ds_read_b128 v[210:213], v197 offset:52224
	ds_read_b128 v[214:217], v197 offset:53248
	ds_read_b128 v[232:235], v197 offset:54272
	ds_read_b128 v[236:239], v197 offset:55296
	ds_read_b128 v[240:243], v197 offset:56320
	global_load_lds_dwordx4 v[184:185], off
	s_add_i32 m0, s14, 0x2000
	s_add_u32 s12, s12, 0x80080
	v_lshl_add_u64 v[184:185], v[190:191], 0, s[46:47]
	s_addc_u32 s13, s13, 0
	s_add_i32 s14, s43, s56
	global_load_lds_dwordx4 v[184:185], off
	v_lshl_add_u64 v[184:185], s[12:13], 0, v[142:143]
	s_mov_b32 m0, s14
	s_nop 0
	global_load_lds_dwordx4 v[184:185], off
	v_lshl_add_u64 v[184:185], s[12:13], 0, v[138:139]
	s_add_i32 m0, s14, 0x2000
	s_nop 0
	global_load_lds_dwordx4 v[184:185], off
	v_lshl_add_u64 v[184:185], v[192:193], 0, s[46:47]
	s_mov_b32 m0, s69
	s_nop 0
	global_load_lds_dwordx4 v[184:185], off
	v_lshl_add_u64 v[184:185], v[194:195], 0, s[46:47]
	s_mov_b32 m0, s70
	s_nop 0
	global_load_lds_dwordx4 v[184:185], off
	s_waitcnt vmcnt(8)
	s_waitcnt lgkmcnt(0)
	s_barrier
	s_setprio 1
	s_waitcnt lgkmcnt(0)
	v_mfma_f32_16x16x32_bf16 v[70:73], v[58:61], v[198:201], v[70:73]
	v_mfma_f32_16x16x32_bf16 v[66:69], v[160:163], v[198:201], v[66:69]
	v_mfma_f32_16x16x32_bf16 v[54:57], v[58:61], v[206:209], v[54:57]
	v_mfma_f32_16x16x32_bf16 v[50:53], v[160:163], v[206:209], v[50:53]
	v_mfma_f32_16x16x32_bf16 v[38:41], v[58:61], v[214:217], v[38:41]
	v_mfma_f32_16x16x32_bf16 v[34:37], v[160:163], v[214:217], v[34:37]
	v_mfma_f32_16x16x32_bf16 v[14:17], v[58:61], v[236:239], v[14:17]
	v_mfma_f32_16x16x32_bf16 v[10:13], v[160:163], v[236:239], v[10:13]
	v_mfma_f32_16x16x32_bf16 v[70:73], v[62:65], v[202:205], v[70:73]
	v_mfma_f32_16x16x32_bf16 v[66:69], v[164:167], v[202:205], v[66:69]
	v_mfma_f32_16x16x32_bf16 v[54:57], v[62:65], v[210:213], v[54:57]
	v_mfma_f32_16x16x32_bf16 v[50:53], v[164:167], v[210:213], v[50:53]
	v_mfma_f32_16x16x32_bf16 v[38:41], v[62:65], v[232:235], v[38:41]
	v_mfma_f32_16x16x32_bf16 v[34:37], v[164:167], v[232:235], v[34:37]
	v_mfma_f32_16x16x32_bf16 v[14:17], v[62:65], v[240:243], v[14:17]
	v_mfma_f32_16x16x32_bf16 v[10:13], v[164:167], v[240:243], v[10:13]
	s_setprio 0
	s_setprio 1
	v_mfma_f32_16x16x32_bf16 v[18:21], v[168:171], v[198:201], v[18:21]
	v_mfma_f32_16x16x32_bf16 v[62:65], v[172:175], v[202:205], v[18:21]
	v_mfma_f32_16x16x32_bf16 v[18:21], v[176:179], v[198:201], v[22:25]
	v_mfma_f32_16x16x32_bf16 v[58:61], v[180:183], v[202:205], v[18:21]
	v_mfma_f32_16x16x32_bf16 v[18:21], v[168:171], v[206:209], v[46:49]
	v_mfma_f32_16x16x32_bf16 v[46:49], v[172:175], v[210:213], v[18:21]
	v_mfma_f32_16x16x32_bf16 v[18:21], v[176:179], v[206:209], v[42:45]
	v_mfma_f32_16x16x32_bf16 v[42:45], v[180:183], v[210:213], v[18:21]
	v_mfma_f32_16x16x32_bf16 v[18:21], v[168:171], v[214:217], v[30:33]
	v_mfma_f32_16x16x32_bf16 v[30:33], v[172:175], v[232:235], v[18:21]
	v_mfma_f32_16x16x32_bf16 v[18:21], v[176:179], v[214:217], v[26:29]
	v_mfma_f32_16x16x32_bf16 v[6:9], v[168:171], v[236:239], v[6:9]
	v_mfma_f32_16x16x32_bf16 v[2:5], v[176:179], v[236:239], v[2:5]
	v_mfma_f32_16x16x32_bf16 v[26:29], v[180:183], v[232:235], v[18:21]
	v_mfma_f32_16x16x32_bf16 v[6:9], v[172:175], v[240:243], v[6:9]
	v_mfma_f32_16x16x32_bf16 v[2:5], v[180:183], v[240:243], v[2:5]
	s_setprio 0
	s_barrier
	s_add_i32 s40, s40, 2
	s_add_u32 s38, s38, 0x100
	s_addc_u32 s39, s39, 0
	s_add_u32 s10, s10, 0x100
	s_addc_u32 s11, s11, 0
	s_cmp_gt_u32 s40, 29
	s_cbranch_scc0 .LBB0_213
	s_and_b64 vcc, exec, s[24:25]
	s_cbranch_vccz .LBB0_216
	s_barrier
